# GEMM phase prologues: the second K-tile's six staging loads are issued together with the first K-tile's, before the first wait (their latency overlaps instead of following the first tile's)
# baseline (speedup 1.0000x reference)
.LBB0_312:
	s_add_u32 s22, s14, 0x200000
	s_addc_u32 s23, s15, 0
	s_add_u32 s24, s14, 0x300000
	s_addc_u32 s25, s15, 0
	s_add_u32 s26, s14, 0x4800000
	s_addc_u32 s27, s15, 0
	s_add_u32 s28, s14, 0x8800000
	s_addc_u32 s29, s15, 0
	s_add_u32 s30, s14, 0xc800000
	s_addc_u32 s31, s15, 0
	s_add_u32 s14, s14, 0x14800000
	s_addc_u32 s15, s15, 0
	s_lshl_b32 s65, s4, 6
	s_lshl_b32 s66, s4, 13
	s_lshl_b32 s4, s5, 5
	s_mov_b64 s[36:37], 0x80
	s_and_b32 s67, s4, 0x60
	s_add_i32 m0, s17, 0x18000
	v_lshl_add_u64 v[6:7], v[6:7], 0, s[36:37]
	s_lshl_b32 s38, s67, 7
	global_load_lds_dwordx4 v[6:7], off
	v_lshl_add_u64 v[4:5], v[4:5], 0, s[36:37]
	s_add_i32 m0, s17, 0x1a000
	s_add_i32 s68, s17, 0x8000
	s_add_i32 s69, s17, 0xa000
	global_load_lds_dwordx4 v[4:5], off
	v_lshl_add_u64 v[0:1], v[0:1], 0, s[36:37]
	s_mov_b32 m0, s68
	s_add_u32 s4, s8, 0x40080
	global_load_lds_dwordx4 v[0:1], off
	v_lshl_add_u64 v[0:1], v[2:3], 0, s[36:37]
	s_mov_b32 m0, s69
	s_addc_u32 s5, s9, 0
	global_load_lds_dwordx4 v[0:1], off
	s_add_i32 m0, s17, 0x1c000
	v_lshl_add_u64 v[0:1], s[4:5], 0, v[162:163]
	global_load_lds_dwordx4 v[0:1], off
	v_lshl_add_u64 v[0:1], s[4:5], 0, v[166:167]
	s_add_i32 m0, s17, 0x1e000
	s_movk_i32 s4, 0x3c0
	global_load_lds_dwordx4 v[0:1], off
	s_waitcnt vmcnt(8)
	s_barrier
	v_and_b32_e32 v0, 48, v8
	v_lshlrev_b32_e32 v1, 6, v8
	v_and_or_b32 v0, v1, s4, v0
	v_lshlrev_b32_e32 v1, 2, v8
	v_and_b32_e32 v1, 32, v1
	v_bitop3_b32 v2, v0, s66, v1 bitop3:0xde
	v_bitop3_b32 v208, s38, v0, v1 bitop3:0xf6
	v_lshlrev_b32_e32 v0, 14, v9
	v_and_b32_e32 v0, 0xffff8000, v0
	v_lshl_add_u32 v0, v10, 11, v0
	v_and_b32_e32 v1, 1, v9
	v_lshl_or_b32 v0, v1, 6, v0
	v_lshl_add_u32 v170, v11, 1, v0
	v_lshlrev_b32_e32 v0, 14, v12
	v_and_b32_e32 v0, 0xffff8000, v0
	s_waitcnt vmcnt(6)
	s_cmpk_lt_u32 s18, 0x100
	v_lshl_add_u32 v0, v13, 11, v0
	v_and_b32_e32 v1, 1, v12
	s_cselect_b64 s[38:39], -1, 0
	v_lshl_or_b32 v0, v1, 6, v0
	s_add_i32 s73, 0, 0x10000
	s_add_i32 s74, 0, 0x14000
	s_movk_i32 s40, 0xe000
	s_add_i32 s70, s66, 0x4000
	s_ashr_i32 s71, s58, 31
	v_mov_b32_e32 v171, v169
	v_lshl_add_u32 v172, v14, 1, v0
	v_mov_b32_e32 v173, v169
	v_mov_b64_e32 v[174:175], 0xc00
	v_mov_b64_e32 v[176:177], 0xbff
	s_movk_i32 s72, 0x181
	v_add_u32_e32 v209, s73, v208
	v_add_u32_e32 v210, s74, v208
	v_add_u32_e32 v211, 0, v2
	v_mov_b32_e32 v212, 0x358637bd
	s_mov_b32 s41, -1
	s_movk_i32 s75, 0xe000
	s_mov_b32 s76, 0xc2fc0000
	v_mov_b32_e32 v213, 0xbbb906ce
	v_mov_b32_e32 v214, 0xbc3963dd
	v_mov_b32_e32 v215, 0x42800000
	v_not_b32_e32 v216, 63
	s_mov_b32 s5, 0
	s_barrier
	s_branch .LBB0_315

.LBB0_688:
	s_add_u32 s14, s16, 0xf800000
	s_addc_u32 s15, s17, 0
	s_add_u32 s16, s16, 0x100000
	s_addc_u32 s17, s17, 0
	s_lshl_b32 s18, s18, 5
	s_mov_b64 s[20:21], 0x80
	s_and_b32 s18, s18, 0x60
	s_add_i32 m0, s56, 0x18000
	v_lshl_add_u64 v[6:7], v[6:7], 0, s[20:21]
	s_lshl_b32 s60, s8, 6
	s_lshl_b32 s24, s8, 13
	s_lshl_b32 s25, s18, 7
	global_load_lds_dwordx4 v[6:7], off
	v_lshl_add_u64 v[4:5], v[4:5], 0, s[20:21]
	s_add_i32 m0, s56, 0x1a000
	s_add_i32 s61, s56, 0x8000
	s_add_i32 s62, s56, 0xa000
	global_load_lds_dwordx4 v[4:5], off
	v_lshl_add_u64 v[0:1], v[0:1], 0, s[20:21]
	s_mov_b32 m0, s61
	s_add_u32 s22, s46, 0x80080
	global_load_lds_dwordx4 v[0:1], off
	v_lshl_add_u64 v[0:1], v[2:3], 0, s[20:21]
	s_mov_b32 m0, s62
	s_addc_u32 s23, s47, 0
	global_load_lds_dwordx4 v[0:1], off
	s_add_i32 m0, s56, 0x1c000
	v_lshl_add_u64 v[0:1], s[22:23], 0, v[176:177]
	global_load_lds_dwordx4 v[0:1], off
	v_lshl_add_u64 v[0:1], s[22:23], 0, v[178:179]
	s_add_i32 m0, s56, 0x1e000
	s_movk_i32 s22, 0x3c0
	global_load_lds_dwordx4 v[0:1], off
	s_waitcnt vmcnt(8)
	s_barrier
	v_and_b32_e32 v0, 48, v8
	v_lshlrev_b32_e32 v1, 6, v8
	v_and_or_b32 v0, v1, s22, v0
	v_lshlrev_b32_e32 v1, 2, v8
	v_and_b32_e32 v1, 32, v1
	v_bitop3_b32 v2, v0, s24, v1 bitop3:0xde
	v_bitop3_b32 v189, s25, v0, v1 bitop3:0xf6
	v_lshlrev_b32_e32 v0, 15, v9
	v_and_b32_e32 v0, 0xffff0000, v0
	v_lshl_add_u32 v0, v10, 12, v0
	v_and_b32_e32 v1, 1, v9
	s_lshl_b32 s63, s8, 10
	v_lshl_or_b32 v0, v1, 6, v0
	s_cmpk_lt_u32 s19, 0x100
	v_lshl_add_u32 v180, v11, 1, v0
	v_lshlrev_b32_e32 v0, 15, v12
	s_cselect_b64 s[22:23], -1, 0
	s_lshl_b32 s8, s18, 2
	v_and_b32_e32 v0, 0xffff0000, v0
	s_waitcnt vmcnt(6)
	s_add_u32 s64, s4, s8
	v_lshl_add_u32 v0, v13, 12, v0
	v_and_b32_e32 v1, 1, v12
	s_addc_u32 s65, s5, 0
	s_add_i32 s66, s63, 0
	v_lshl_or_b32 v0, v1, 6, v0
	s_add_i32 s67, 0, 0x14000
	s_add_i32 s68, 0, 0x10000
	s_mov_b32 s19, s9
	s_add_i32 s66, s66, 0x203fd
	v_mov_b32_e32 v181, v177
	v_lshl_add_u32 v182, v14, 1, v0
	v_mov_b32_e32 v183, v177
	v_add_u32_e32 v195, s67, v189
	v_add_u32_e32 v203, s68, v189
	v_add_u32_e32 v211, 0, v2
	s_mov_b64 s[24:25], 0x100
	s_mov_b64 s[26:27], 0x180
	s_mov_b32 s69, 0
	s_mov_b32 s41, 0
	s_barrier
	s_branch .LBB0_691

.LBB0_778:
	s_add_u32 s12, s4, 0x100000
	s_addc_u32 s13, s5, 0
	s_add_u32 s14, s4, 0x4800000
	s_addc_u32 s15, s5, 0
	s_lshl_b32 s56, s17, 6
	s_lshl_b32 s19, s17, 13
	s_lshl_b32 s4, s16, 5
	s_mov_b64 s[16:17], 0x80
	s_and_b32 s20, s4, 0x60
	s_add_i32 m0, s50, 0x18000
	v_lshl_add_u64 v[6:7], v[6:7], 0, s[16:17]
	s_lshl_b32 s22, s20, 7
	global_load_lds_dwordx4 v[6:7], off
	v_lshl_add_u64 v[4:5], v[4:5], 0, s[16:17]
	s_add_i32 m0, s50, 0x1a000
	s_add_i32 s57, s50, 0x8000
	s_add_i32 s58, s50, 0xa000
	global_load_lds_dwordx4 v[4:5], off
	v_lshl_add_u64 v[0:1], v[0:1], 0, s[16:17]
	s_mov_b32 m0, s57
	s_add_u32 s4, s38, 0x40080
	global_load_lds_dwordx4 v[0:1], off
	v_lshl_add_u64 v[0:1], v[2:3], 0, s[16:17]
	s_mov_b32 m0, s58
	s_addc_u32 s5, s39, 0
	global_load_lds_dwordx4 v[0:1], off
	s_add_i32 m0, s50, 0x1c000
	v_lshl_add_u64 v[0:1], s[4:5], 0, v[132:133]
	global_load_lds_dwordx4 v[0:1], off
	v_lshl_add_u64 v[0:1], s[4:5], 0, v[128:129]
	s_add_i32 m0, s50, 0x1e000
	s_movk_i32 s4, 0x3c0
	global_load_lds_dwordx4 v[0:1], off
	s_waitcnt vmcnt(8)
	s_barrier
	v_and_b32_e32 v0, 48, v8
	v_lshlrev_b32_e32 v1, 6, v8
	v_and_or_b32 v0, v1, s4, v0
	v_lshlrev_b32_e32 v1, 2, v8
	v_and_b32_e32 v1, 32, v1
	v_bitop3_b32 v2, v0, s19, v1 bitop3:0xde
	v_bitop3_b32 v162, s22, v0, v1 bitop3:0xf6
	v_lshlrev_b32_e32 v0, 14, v13
	v_and_b32_e32 v0, 0xffff8000, v0
	v_lshl_add_u32 v0, v12, 11, v0
	v_and_b32_e32 v1, 1, v13
	v_lshl_or_b32 v0, v1, 6, v0
	v_lshl_add_u32 v136, v14, 1, v0
	v_lshlrev_b32_e32 v0, 14, v9
	v_and_b32_e32 v0, 0xffff8000, v0
	s_waitcnt vmcnt(6)
	s_cmpk_lt_u32 s18, 0x100
	v_lshl_add_u32 v0, v10, 11, v0
	v_and_b32_e32 v1, 1, v9
	s_cselect_b64 s[18:19], -1, 0
	v_lshl_or_b32 v0, v1, 6, v0
	s_add_i32 s59, 0, 0x10000
	s_add_i32 s60, 0, 0x14000
	s_sext_i32_i16 s21, s6
	v_mov_b32_e32 v137, v133
	v_lshl_add_u32 v138, v11, 1, v0
	v_mov_b32_e32 v139, v133
	v_mov_b64_e32 v[140:141], 0xb00
	v_mov_b64_e32 v[142:143], 0xaff
	v_add_u32_e32 v163, s59, v162
	v_add_u32_e32 v164, s60, v162
	v_add_u32_e32 v165, 0, v2
	v_mov_b32_e32 v166, 0x358637bd
	s_movk_i32 s61, 0x1600
	s_lshl_b32 s20, s20, 1
	s_mov_b32 s6, s7
	s_barrier
	s_branch .LBB0_781

.LBB0_852:
	s_add_u32 s14, s4, 0x14800000
	s_addc_u32 s15, s5, 0
	s_add_u32 s16, s4, 0x120000
	s_addc_u32 s17, s5, 0
	s_lshl_b32 s7, s7, 5
	s_mov_b64 s[20:21], 0x80
	s_and_b32 s18, s7, 0x60
	s_add_i32 m0, s44, 0x18000
	v_lshl_add_u64 v[6:7], v[6:7], 0, s[20:21]
	s_lshl_b32 s48, s8, 6
	s_lshl_b32 s8, s8, 13
	s_lshl_b32 s7, s18, 7
	global_load_lds_dwordx4 v[6:7], off
	v_lshl_add_u64 v[4:5], v[4:5], 0, s[20:21]
	s_add_i32 m0, s44, 0x1a000
	s_add_i32 s49, s44, 0x8000
	s_add_i32 s50, s44, 0xa000
	global_load_lds_dwordx4 v[4:5], off
	v_lshl_add_u64 v[0:1], v[0:1], 0, s[20:21]
	s_mov_b32 m0, s49
	s_add_u32 s22, s28, 0xb0080
	global_load_lds_dwordx4 v[0:1], off
	v_lshl_add_u64 v[0:1], v[2:3], 0, s[20:21]
	s_mov_b32 m0, s50
	s_addc_u32 s23, s29, 0
	global_load_lds_dwordx4 v[0:1], off
	s_add_i32 m0, s44, 0x1c000
	v_lshl_add_u64 v[0:1], s[22:23], 0, v[186:187]
	global_load_lds_dwordx4 v[0:1], off
	v_lshl_add_u64 v[0:1], s[22:23], 0, v[190:191]
	s_add_i32 m0, s44, 0x1e000
	s_movk_i32 s22, 0x3c0
	global_load_lds_dwordx4 v[0:1], off
	s_waitcnt vmcnt(8)
	s_barrier
	v_and_b32_e32 v0, 48, v8
	v_lshlrev_b32_e32 v1, 6, v8
	v_and_or_b32 v0, v1, s22, v0
	v_lshlrev_b32_e32 v1, 2, v8
	v_and_b32_e32 v1, 32, v1
	s_cmpk_lt_u32 s19, 0x100
	v_bitop3_b32 v232, s7, v0, v1 bitop3:0xf6
	s_cselect_b64 s[22:23], -1, 0
	s_ashr_i32 s51, s38, 31
	s_lshl_b32 s7, s18, 1
	s_add_u32 s4, s4, s7
	s_addc_u32 s5, s5, 0
	v_bitop3_b32 v2, v0, s8, v1 bitop3:0xde
	s_add_u32 s54, s4, 0xf800000
	v_lshrrev_b32_e32 v1, 1, v9
	v_mul_lo_u32 v0, v11, s6
	s_mov_b32 s7, 0xb000
	s_addc_u32 s55, s5, 0
	v_mad_u64_u32 v[0:1], s[4:5], v1, s7, v[0:1]
	v_or_b32_e32 v0, v0, v10
	s_mov_b64 s[24:25], 0xb0080
	v_add_lshl_u32 v0, v0, v12, 1
	v_mov_b32_e32 v1, v187
	v_lshl_add_u64 v[192:193], v[0:1], 0, s[24:25]
	v_lshrrev_b32_e32 v1, 1, v13
	v_mul_lo_u32 v0, v14, s6
	v_mad_u64_u32 v[0:1], s[4:5], v1, s7, v[0:1]
	s_waitcnt vmcnt(6)
	v_or_b32_e32 v0, v0, v15
	v_add_lshl_u32 v0, v0, v16, 1
	v_mov_b32_e32 v1, v187
	s_add_i32 s56, 0, 0x10000
	s_add_i32 s57, 0, 0x14000
	s_mov_b32 s19, s9
	v_lshl_add_u64 v[194:195], v[0:1], 0, s[24:25]
	v_mov_b64_e32 v[196:197], 0x200
	v_mov_b64_e32 v[198:199], 0x1ff
	v_add_u32_e32 v233, s56, v232
	v_add_u32_e32 v234, s57, v232
	v_add_u32_e32 v235, 0, v2
	s_mov_b32 s8, s9
	s_barrier
	s_branch .LBB0_855

.LBB0_946:
	s_add_u32 s18, s22, 0x120000
	s_addc_u32 s19, s23, 0
	s_add_u32 s58, s22, 0x4800000
	s_addc_u32 s59, s23, 0
	s_add_u32 s20, s22, 0x8800000
	s_addc_u32 s21, s23, 0
	s_add_u32 s60, s22, 0xc800000
	s_addc_u32 s61, s23, 0
	s_mov_b64 s[22:23], 0x80
	s_and_b32 s26, s24, 3
	s_add_i32 m0, s54, 0x18000
	v_lshl_add_u64 v[6:7], v[6:7], 0, s[22:23]
	s_lshl_b32 s62, s25, 6
	s_lshl_b32 s24, s25, 13
	s_lshl_b32 s63, s26, 5
	s_lshl_b32 s25, s26, 12
	global_load_lds_dwordx4 v[6:7], off
	v_lshl_add_u64 v[4:5], v[4:5], 0, s[22:23]
	s_add_i32 m0, s54, 0x1a000
	s_add_i32 s64, s54, 0x8000
	s_add_i32 s65, s54, 0xa000
	global_load_lds_dwordx4 v[4:5], off
	v_lshl_add_u64 v[0:1], v[0:1], 0, s[22:23]
	s_mov_b32 m0, s64
	s_add_u32 s4, s40, 0x40080
	global_load_lds_dwordx4 v[0:1], off
	v_lshl_add_u64 v[0:1], v[2:3], 0, s[22:23]
	s_mov_b32 m0, s65
	s_addc_u32 s5, s41, 0
	global_load_lds_dwordx4 v[0:1], off
	s_add_i32 m0, s54, 0x1c000
	v_lshl_add_u64 v[0:1], s[4:5], 0, v[130:131]
	global_load_lds_dwordx4 v[0:1], off
	v_lshl_add_u64 v[0:1], s[4:5], 0, v[134:135]
	s_add_i32 m0, s54, 0x1e000
	s_movk_i32 s4, 0x3c0
	global_load_lds_dwordx4 v[0:1], off
	s_waitcnt vmcnt(8)
	s_barrier
	v_and_b32_e32 v0, 48, v8
	v_lshlrev_b32_e32 v1, 6, v8
	v_and_or_b32 v0, v1, s4, v0
	v_lshlrev_b32_e32 v1, 2, v8
	v_and_b32_e32 v1, 32, v1
	v_bitop3_b32 v2, v0, s24, v1 bitop3:0xde
	v_bitop3_b32 v178, s25, v0, v1 bitop3:0xf6
	v_lshlrev_b32_e32 v0, 14, v9
	v_and_b32_e32 v0, 0xffff8000, v0
	v_lshl_add_u32 v0, v10, 11, v0
	v_and_b32_e32 v1, 1, v9
	v_lshl_or_b32 v0, v1, 6, v0
	v_lshl_add_u32 v136, v11, 1, v0
	v_lshlrev_b32_e32 v0, 14, v12
	v_and_b32_e32 v0, 0xffff8000, v0
	s_waitcnt vmcnt(6)
	s_cmpk_lt_u32 s14, 0x100
	v_lshl_add_u32 v0, v13, 11, v0
	v_and_b32_e32 v1, 1, v12
	s_cselect_b64 s[24:25], -1, 0
	v_lshl_or_b32 v0, v1, 6, v0
	s_add_i32 s69, 0, 0x10000
	s_add_i32 s70, 0, 0x14000
	s_lshl_b32 s66, s26, 6
	s_ashr_i32 s67, s46, 31
	v_mov_b32_e32 v137, v131
	v_lshl_add_u32 v138, v14, 1, v0
	v_mov_b32_e32 v139, v131
	v_mov_b64_e32 v[140:141], 0x600
	v_mov_b64_e32 v[142:143], 0x5ff
	s_movk_i32 s68, 0xc1
	v_add_u32_e32 v179, s69, v178
	v_add_u32_e32 v180, s70, v178
	v_add_u32_e32 v181, 0, v2
	v_mov_b32_e32 v182, 0x358637bd
	v_mov_b32_e32 v183, 0x3e38aa3b
	s_mov_b32 s14, s15
	s_barrier
	s_branch .LBB0_949

.LBB0_1136:
	s_add_u32 s12, s4, 0x14800000
	s_addc_u32 s13, s5, 0
	s_add_u32 s14, s4, 0x140000
	s_addc_u32 s15, s5, 0
	s_lshl_b32 s4, s6, 5
	s_mov_b64 s[18:19], 0x80
	s_lshl_b32 s56, s16, 6
	s_lshl_b32 s20, s16, 13
	s_and_b32 s16, s4, 0x60
	s_add_i32 m0, s50, 0x18000
	v_lshl_add_u64 v[6:7], v[6:7], 0, s[18:19]
	s_lshl_b32 s6, s16, 7
	global_load_lds_dwordx4 v[6:7], off
	v_lshl_add_u64 v[4:5], v[4:5], 0, s[18:19]
	s_add_i32 m0, s50, 0x1a000
	s_add_i32 s57, s50, 0x8000
	s_add_i32 s58, s50, 0xa000
	global_load_lds_dwordx4 v[4:5], off
	v_lshl_add_u64 v[0:1], v[0:1], 0, s[18:19]
	s_mov_b32 m0, s57
	s_add_u32 s4, s40, 0x40080
	global_load_lds_dwordx4 v[0:1], off
	v_lshl_add_u64 v[0:1], v[2:3], 0, s[18:19]
	s_mov_b32 m0, s58
	s_addc_u32 s5, s41, 0
	global_load_lds_dwordx4 v[0:1], off
	s_add_i32 m0, s50, 0x1c000
	v_lshl_add_u64 v[0:1], s[4:5], 0, v[186:187]
	global_load_lds_dwordx4 v[0:1], off
	v_lshl_add_u64 v[0:1], s[4:5], 0, v[190:191]
	s_add_i32 m0, s50, 0x1e000
	s_movk_i32 s4, 0x3c0
	global_load_lds_dwordx4 v[0:1], off
	s_waitcnt vmcnt(8)
	s_barrier
	v_and_b32_e32 v0, 48, v8
	v_lshlrev_b32_e32 v1, 6, v8
	v_and_or_b32 v0, v1, s4, v0
	v_lshlrev_b32_e32 v1, 2, v8
	v_and_b32_e32 v1, 32, v1
	v_bitop3_b32 v2, v0, s20, v1 bitop3:0xde
	v_bitop3_b32 v232, s6, v0, v1 bitop3:0xf6
	v_lshlrev_b32_e32 v0, 14, v9
	v_and_b32_e32 v0, 0xffff8000, v0
	v_lshl_add_u32 v0, v10, 11, v0
	v_and_b32_e32 v1, 1, v9
	v_lshl_or_b32 v0, v1, 6, v0
	s_cmpk_lt_u32 s17, 0x100
	v_lshl_add_u32 v192, v11, 1, v0
	v_lshlrev_b32_e32 v0, 14, v12
	s_cselect_b64 s[20:21], -1, 0
	s_ashr_i32 s59, s44, 31
	s_lshl_b32 s4, s16, 1
	v_and_b32_e32 v0, 0xffff8000, v0
	s_waitcnt vmcnt(6)
	s_add_u32 s60, s12, s4
	v_lshl_add_u32 v0, v13, 11, v0
	v_and_b32_e32 v1, 1, v12
	s_addc_u32 s61, s13, 0
	v_lshl_or_b32 v0, v1, 6, v0
	s_add_i32 s62, 0, 0x10000
	s_add_i32 s63, 0, 0x14000
	s_mov_b32 s17, s7
	v_mov_b32_e32 v193, v187
	v_lshl_add_u32 v194, v14, 1, v0
	v_mov_b32_e32 v195, v187
	v_mov_b64_e32 v[196:197], 0x200
	v_mov_b64_e32 v[198:199], 0x1ff
	v_add_u32_e32 v233, s62, v232
	v_add_u32_e32 v234, s63, v232
	v_add_u32_e32 v235, 0, v2
	s_mov_b32 s6, s7
	s_barrier
	s_branch .LBB0_1139

.LBB0_1224:
	s_add_u32 s12, s4, 0x140000
	s_addc_u32 s13, s5, 0
	s_add_u32 s14, s4, 0x4800000
	s_addc_u32 s15, s5, 0
	s_lshl_b32 s56, s17, 6
	s_lshl_b32 s19, s17, 13
	s_lshl_b32 s4, s16, 5
	s_mov_b64 s[16:17], 0x80
	s_and_b32 s20, s4, 0x60
	s_add_i32 m0, s50, 0x18000
	v_lshl_add_u64 v[6:7], v[6:7], 0, s[16:17]
	s_lshl_b32 s22, s20, 7
	global_load_lds_dwordx4 v[6:7], off
	v_lshl_add_u64 v[4:5], v[4:5], 0, s[16:17]
	s_add_i32 m0, s50, 0x1a000
	s_add_i32 s57, s50, 0x8000
	s_add_i32 s58, s50, 0xa000
	global_load_lds_dwordx4 v[4:5], off
	v_lshl_add_u64 v[0:1], v[0:1], 0, s[16:17]
	s_mov_b32 m0, s57
	s_add_u32 s4, s38, 0x40080
	global_load_lds_dwordx4 v[0:1], off
	v_lshl_add_u64 v[0:1], v[2:3], 0, s[16:17]
	s_mov_b32 m0, s58
	s_addc_u32 s5, s39, 0
	global_load_lds_dwordx4 v[0:1], off
	s_add_i32 m0, s50, 0x1c000
	v_lshl_add_u64 v[0:1], s[4:5], 0, v[132:133]
	global_load_lds_dwordx4 v[0:1], off
	v_lshl_add_u64 v[0:1], s[4:5], 0, v[128:129]
	s_add_i32 m0, s50, 0x1e000
	s_movk_i32 s4, 0x3c0
	global_load_lds_dwordx4 v[0:1], off
	s_waitcnt vmcnt(8)
	s_barrier
	v_and_b32_e32 v0, 48, v8
	v_lshlrev_b32_e32 v1, 6, v8
	v_and_or_b32 v0, v1, s4, v0
	v_lshlrev_b32_e32 v1, 2, v8
	v_and_b32_e32 v1, 32, v1
	v_bitop3_b32 v2, v0, s19, v1 bitop3:0xde
	v_bitop3_b32 v162, s22, v0, v1 bitop3:0xf6
	v_lshlrev_b32_e32 v0, 14, v13
	v_and_b32_e32 v0, 0xffff8000, v0
	v_lshl_add_u32 v0, v12, 11, v0
	v_and_b32_e32 v1, 1, v13
	v_lshl_or_b32 v0, v1, 6, v0
	v_lshl_add_u32 v136, v14, 1, v0
	v_lshlrev_b32_e32 v0, 14, v9
	v_and_b32_e32 v0, 0xffff8000, v0
	s_waitcnt vmcnt(6)
	s_cmpk_lt_u32 s18, 0x100
	v_lshl_add_u32 v0, v10, 11, v0
	v_and_b32_e32 v1, 1, v9
	s_cselect_b64 s[18:19], -1, 0
	v_lshl_or_b32 v0, v1, 6, v0
	s_add_i32 s59, 0, 0x10000
	s_add_i32 s60, 0, 0x14000
	s_sext_i32_i16 s21, s6
	v_mov_b32_e32 v137, v133
	v_lshl_add_u32 v138, v11, 1, v0
	v_mov_b32_e32 v139, v133
	v_mov_b64_e32 v[140:141], 0xb00
	v_mov_b64_e32 v[142:143], 0xaff
	v_add_u32_e32 v163, s59, v162
	v_add_u32_e32 v164, s60, v162
	v_add_u32_e32 v165, 0, v2
	v_mov_b32_e32 v166, 0x358637bd
	s_movk_i32 s61, 0x1600
	s_lshl_b32 s20, s20, 1
	s_mov_b32 s6, s7
	s_barrier
	s_branch .LBB0_1227

.LBB0_1296:
	s_lshl_b32 s1, s1, 5
	s_mov_b64 s[16:17], 0x80
	s_and_b32 s14, s1, 0x60
	s_add_i32 m0, s36, 0x18000
	v_lshl_add_u64 v[6:7], v[6:7], 0, s[16:17]
	s_lshl_b32 s40, s5, 6
	s_lshl_b32 s5, s5, 13
	s_lshl_b32 s1, s14, 7
	global_load_lds_dwordx4 v[6:7], off
	v_lshl_add_u64 v[4:5], v[4:5], 0, s[16:17]
	s_add_i32 m0, s36, 0x1a000
	s_add_i32 s41, s36, 0x8000
	s_add_i32 s42, s36, 0xa000
	global_load_lds_dwordx4 v[4:5], off
	v_lshl_add_u64 v[0:1], v[0:1], 0, s[16:17]
	s_mov_b32 m0, s41
	s_add_u32 s18, s26, 0xb0080
	global_load_lds_dwordx4 v[0:1], off
	v_lshl_add_u64 v[0:1], v[2:3], 0, s[16:17]
	s_mov_b32 m0, s42
	s_addc_u32 s19, s27, 0
	global_load_lds_dwordx4 v[0:1], off
	s_add_i32 m0, s36, 0x1c000
	v_lshl_add_u64 v[0:1], s[18:19], 0, v[166:167]
	global_load_lds_dwordx4 v[0:1], off
	v_lshl_add_u64 v[0:1], s[18:19], 0, v[170:171]
	s_add_i32 m0, s36, 0x1e000
	s_sext_i32_i8 s50, s4
	global_load_lds_dwordx4 v[0:1], off
	s_waitcnt vmcnt(8)
	s_barrier
	v_and_b32_e32 v0, 48, v8
	v_lshlrev_b32_e32 v1, 6, v8
	s_movk_i32 s4, 0x3c0
	v_and_or_b32 v0, v1, s4, v0
	v_lshlrev_b32_e32 v1, 2, v8
	v_and_b32_e32 v1, 32, v1
	s_cmpk_lt_u32 s6, 0x100
	v_bitop3_b32 v196, s1, v0, v1 bitop3:0xf6
	s_cselect_b64 s[18:19], -1, 0
	s_lshl_b32 s1, s14, 1
	s_add_u32 s1, s10, s1
	s_addc_u32 s6, s11, 0
	v_bitop3_b32 v2, v0, s5, v1 bitop3:0xde
	s_add_u32 s43, s1, 0x14800000
	v_lshrrev_b32_e32 v1, 1, v9
	v_mul_lo_u32 v0, v11, s0
	s_mov_b32 s1, 0xb000
	v_mad_u64_u32 v[0:1], s[20:21], v1, s1, v[0:1]
	v_or_b32_e32 v0, v0, v10
	s_mov_b64 s[4:5], 0xb0080
	v_add_lshl_u32 v0, v0, v12, 1
	v_mov_b32_e32 v1, v167
	v_lshl_add_u64 v[172:173], v[0:1], 0, s[4:5]
	v_lshrrev_b32_e32 v1, 1, v13
	v_mul_lo_u32 v0, v14, s0
	s_addc_u32 s44, s6, 0
	v_mad_u64_u32 v[0:1], s[0:1], v1, s1, v[0:1]
	s_waitcnt vmcnt(6)
	s_cmp_lg_u64 s[8:9], 0
	v_or_b32_e32 v0, v0, v15
	s_cselect_b64 s[10:11], -1, 0
	v_add_lshl_u32 v0, v0, v16, 1
	v_mov_b32_e32 v1, v167
	s_add_i32 s45, 0, 0x10000
	s_add_i32 s46, 0, 0x14000
	s_mov_b32 s15, s7
	v_lshl_add_u64 v[174:175], v[0:1], 0, s[4:5]
	v_mov_b64_e32 v[176:177], 0x200
	v_mov_b64_e32 v[178:179], 0x1ff
	v_add_u32_e32 v197, s45, v196
	v_add_u32_e32 v198, s46, v196
	v_add_u32_e32 v199, 0, v2
	s_mov_b32 s6, s7
	s_barrier
	s_branch .LBB0_1299
